# strategy 2 (de-serialisation): prep0 silu(conditioning) table: 12 loads issued together instead of a divergent one-load-one-wait loop
# speedup vs baseline: 1.0048x; 1.0048x over previous
.LBB0_450:
	s_and_b64 vcc, exec, s[8:9]
	s_cbranch_vccz .LBB0_7
	v_readfirstlane_b32 s0, v137
	s_lshr_b32 s5, s0, 8
	s_mov_b64 s[42:43], 0
	s_mov_b64 s[0:1], 0
	s_mul_i32 s5, s5, 0x12000
	v_mov_b32_e32 v26, v139
	s_movk_i32 s0, 0xc00
	s_nop 0
	v_cmp_gt_i32_e32 vcc, s0, v26
	v_lshl_add_u32 v27, v26, 2, s5
	s_and_saveexec_b64 s[0:1], vcc
	s_movk_i32 s11, 0x3ff
	s_cbranch_execz .LBB0_458
	v_readlane_b32 s56, v254, 53
	v_readlane_b32 s57, v254, 54
	v_readlane_b32 s58, v254, 55
	v_readlane_b32 s59, v254, 56
	v_readlane_b32 s60, v254, 57
	v_readlane_b32 s61, v254, 58
	v_readlane_b32 s62, v254, 59
	v_readlane_b32 s63, v254, 60
	v_readlane_b32 s64, v254, 61
	v_readlane_b32 s65, v254, 62
	v_readlane_b32 s66, v254, 63
	v_readlane_b32 s67, v255, 0
	v_readlane_b32 s70, v255, 3
	v_readlane_b32 s71, v255, 4
	s_mov_b64 s[68:69], 0x7b54180
	v_lshlrev_b32_e32 v10, 2, v26
	v_add_u32_e32 v11, 0x1000, v10
	s_nop 4
	global_load_dword v40, v10, s[60:61]
	global_load_dword v41, v10, s[60:61] offset:1024
	global_load_dword v42, v10, s[60:61] offset:2048
	global_load_dword v43, v10, s[60:61] offset:3072
	global_load_dword v44, v10, s[58:59]
	global_load_dword v45, v10, s[58:59] offset:1024
	global_load_dword v46, v10, s[58:59] offset:2048
	global_load_dword v47, v10, s[58:59] offset:3072
	global_load_dword v48, v11, s[58:59]
	global_load_dword v49, v11, s[58:59] offset:1024
	global_load_dword v50, v11, s[58:59] offset:2048
	global_load_dword v51, v11, s[58:59] offset:3072
	s_waitcnt vmcnt(0)
	v_mul_f32_e32 v2, 0xbfb8aa3b, v40
	v_exp_f32_e32 v2, v2
	s_nop 0
	v_add_f32_e32 v2, 1.0, v2
	v_div_scale_f32 v3, s[8:9], v2, v2, v40
	v_rcp_f32_e32 v6, v3
	s_nop 0
	v_fma_f32 v7, -v3, v6, 1.0
	v_fmac_f32_e32 v6, v7, v6
	v_div_scale_f32 v7, vcc, v40, v2, v40
	v_mul_f32_e32 v8, v7, v6
	v_fma_f32 v9, -v3, v8, v7
	v_fmac_f32_e32 v8, v9, v6
	v_fma_f32 v3, -v3, v8, v7
	v_div_fmas_f32 v3, v3, v6, v8
	v_div_fixup_f32 v0, v3, v2, v40
	ds_write_b32 v27, v0
	v_mul_f32_e32 v2, 0xbfb8aa3b, v41
	v_exp_f32_e32 v2, v2
	s_nop 0
	v_add_f32_e32 v2, 1.0, v2
	v_div_scale_f32 v3, s[8:9], v2, v2, v41
	v_rcp_f32_e32 v6, v3
	s_nop 0
	v_fma_f32 v7, -v3, v6, 1.0
	v_fmac_f32_e32 v6, v7, v6
	v_div_scale_f32 v7, vcc, v41, v2, v41
	v_mul_f32_e32 v8, v7, v6
	v_fma_f32 v9, -v3, v8, v7
	v_fmac_f32_e32 v8, v9, v6
	v_fma_f32 v3, -v3, v8, v7
	v_div_fmas_f32 v3, v3, v6, v8
	v_div_fixup_f32 v0, v3, v2, v41
	ds_write_b32 v27, v0 offset:1024
	v_mul_f32_e32 v2, 0xbfb8aa3b, v42
	v_exp_f32_e32 v2, v2
	s_nop 0
	v_add_f32_e32 v2, 1.0, v2
	v_div_scale_f32 v3, s[8:9], v2, v2, v42
	v_rcp_f32_e32 v6, v3
	s_nop 0
	v_fma_f32 v7, -v3, v6, 1.0
	v_fmac_f32_e32 v6, v7, v6
	v_div_scale_f32 v7, vcc, v42, v2, v42
	v_mul_f32_e32 v8, v7, v6
	v_fma_f32 v9, -v3, v8, v7
	v_fmac_f32_e32 v8, v9, v6
	v_fma_f32 v3, -v3, v8, v7
	v_div_fmas_f32 v3, v3, v6, v8
	v_div_fixup_f32 v0, v3, v2, v42
	ds_write_b32 v27, v0 offset:2048
	v_mul_f32_e32 v2, 0xbfb8aa3b, v43
	v_exp_f32_e32 v2, v2
	s_nop 0
	v_add_f32_e32 v2, 1.0, v2
	v_div_scale_f32 v3, s[8:9], v2, v2, v43
	v_rcp_f32_e32 v6, v3
	s_nop 0
	v_fma_f32 v7, -v3, v6, 1.0
	v_fmac_f32_e32 v6, v7, v6
	v_div_scale_f32 v7, vcc, v43, v2, v43
	v_mul_f32_e32 v8, v7, v6
	v_fma_f32 v9, -v3, v8, v7
	v_fmac_f32_e32 v8, v9, v6
	v_fma_f32 v3, -v3, v8, v7
	v_div_fmas_f32 v3, v3, v6, v8
	v_div_fixup_f32 v0, v3, v2, v43
	ds_write_b32 v27, v0 offset:3072
	v_mul_f32_e32 v2, 0xbfb8aa3b, v44
	v_exp_f32_e32 v2, v2
	s_nop 0
	v_add_f32_e32 v2, 1.0, v2
	v_div_scale_f32 v3, s[8:9], v2, v2, v44
	v_rcp_f32_e32 v6, v3
	s_nop 0
	v_fma_f32 v7, -v3, v6, 1.0
	v_fmac_f32_e32 v6, v7, v6
	v_div_scale_f32 v7, vcc, v44, v2, v44
	v_mul_f32_e32 v8, v7, v6
	v_fma_f32 v9, -v3, v8, v7
	v_fmac_f32_e32 v8, v9, v6
	v_fma_f32 v3, -v3, v8, v7
	v_div_fmas_f32 v3, v3, v6, v8
	v_div_fixup_f32 v0, v3, v2, v44
	ds_write_b32 v27, v0 offset:4096
	v_mul_f32_e32 v2, 0xbfb8aa3b, v45
	v_exp_f32_e32 v2, v2
	s_nop 0
	v_add_f32_e32 v2, 1.0, v2
	v_div_scale_f32 v3, s[8:9], v2, v2, v45
	v_rcp_f32_e32 v6, v3
	s_nop 0
	v_fma_f32 v7, -v3, v6, 1.0
	v_fmac_f32_e32 v6, v7, v6
	v_div_scale_f32 v7, vcc, v45, v2, v45
	v_mul_f32_e32 v8, v7, v6
	v_fma_f32 v9, -v3, v8, v7
	v_fmac_f32_e32 v8, v9, v6
	v_fma_f32 v3, -v3, v8, v7
	v_div_fmas_f32 v3, v3, v6, v8
	v_div_fixup_f32 v0, v3, v2, v45
	ds_write_b32 v27, v0 offset:5120
	v_mul_f32_e32 v2, 0xbfb8aa3b, v46
	v_exp_f32_e32 v2, v2
	s_nop 0
	v_add_f32_e32 v2, 1.0, v2
	v_div_scale_f32 v3, s[8:9], v2, v2, v46
	v_rcp_f32_e32 v6, v3
	s_nop 0
	v_fma_f32 v7, -v3, v6, 1.0
	v_fmac_f32_e32 v6, v7, v6
	v_div_scale_f32 v7, vcc, v46, v2, v46
	v_mul_f32_e32 v8, v7, v6
	v_fma_f32 v9, -v3, v8, v7
	v_fmac_f32_e32 v8, v9, v6
	v_fma_f32 v3, -v3, v8, v7
	v_div_fmas_f32 v3, v3, v6, v8
	v_div_fixup_f32 v0, v3, v2, v46
	ds_write_b32 v27, v0 offset:6144
	v_mul_f32_e32 v2, 0xbfb8aa3b, v47
	v_exp_f32_e32 v2, v2
	s_nop 0
	v_add_f32_e32 v2, 1.0, v2
	v_div_scale_f32 v3, s[8:9], v2, v2, v47
	v_rcp_f32_e32 v6, v3
	s_nop 0
	v_fma_f32 v7, -v3, v6, 1.0
	v_fmac_f32_e32 v6, v7, v6
	v_div_scale_f32 v7, vcc, v47, v2, v47
	v_mul_f32_e32 v8, v7, v6
	v_fma_f32 v9, -v3, v8, v7
	v_fmac_f32_e32 v8, v9, v6
	v_fma_f32 v3, -v3, v8, v7
	v_div_fmas_f32 v3, v3, v6, v8
	v_div_fixup_f32 v0, v3, v2, v47
	ds_write_b32 v27, v0 offset:7168
	v_mul_f32_e32 v2, 0xbfb8aa3b, v48
	v_exp_f32_e32 v2, v2
	s_nop 0
	v_add_f32_e32 v2, 1.0, v2
	v_div_scale_f32 v3, s[8:9], v2, v2, v48
	v_rcp_f32_e32 v6, v3
	s_nop 0
	v_fma_f32 v7, -v3, v6, 1.0
	v_fmac_f32_e32 v6, v7, v6
	v_div_scale_f32 v7, vcc, v48, v2, v48
	v_mul_f32_e32 v8, v7, v6
	v_fma_f32 v9, -v3, v8, v7
	v_fmac_f32_e32 v8, v9, v6
	v_fma_f32 v3, -v3, v8, v7
	v_div_fmas_f32 v3, v3, v6, v8
	v_div_fixup_f32 v0, v3, v2, v48
	ds_write_b32 v27, v0 offset:8192
	v_mul_f32_e32 v2, 0xbfb8aa3b, v49
	v_exp_f32_e32 v2, v2
	s_nop 0
	v_add_f32_e32 v2, 1.0, v2
	v_div_scale_f32 v3, s[8:9], v2, v2, v49
	v_rcp_f32_e32 v6, v3
	s_nop 0
	v_fma_f32 v7, -v3, v6, 1.0
	v_fmac_f32_e32 v6, v7, v6
	v_div_scale_f32 v7, vcc, v49, v2, v49
	v_mul_f32_e32 v8, v7, v6
	v_fma_f32 v9, -v3, v8, v7
	v_fmac_f32_e32 v8, v9, v6
	v_fma_f32 v3, -v3, v8, v7
	v_div_fmas_f32 v3, v3, v6, v8
	v_div_fixup_f32 v0, v3, v2, v49
	ds_write_b32 v27, v0 offset:9216
	v_mul_f32_e32 v2, 0xbfb8aa3b, v50
	v_exp_f32_e32 v2, v2
	s_nop 0
	v_add_f32_e32 v2, 1.0, v2
	v_div_scale_f32 v3, s[8:9], v2, v2, v50
	v_rcp_f32_e32 v6, v3
	s_nop 0
	v_fma_f32 v7, -v3, v6, 1.0
	v_fmac_f32_e32 v6, v7, v6
	v_div_scale_f32 v7, vcc, v50, v2, v50
	v_mul_f32_e32 v8, v7, v6
	v_fma_f32 v9, -v3, v8, v7
	v_fmac_f32_e32 v8, v9, v6
	v_fma_f32 v3, -v3, v8, v7
	v_div_fmas_f32 v3, v3, v6, v8
	v_div_fixup_f32 v0, v3, v2, v50
	ds_write_b32 v27, v0 offset:10240
	v_mul_f32_e32 v2, 0xbfb8aa3b, v51
	v_exp_f32_e32 v2, v2
	s_nop 0
	v_add_f32_e32 v2, 1.0, v2
	v_div_scale_f32 v3, s[8:9], v2, v2, v51
	v_rcp_f32_e32 v6, v3
	s_nop 0
	v_fma_f32 v7, -v3, v6, 1.0
	v_fmac_f32_e32 v6, v7, v6
	v_div_scale_f32 v7, vcc, v51, v2, v51
	v_mul_f32_e32 v8, v7, v6
	v_fma_f32 v9, -v3, v8, v7
	v_fmac_f32_e32 v8, v9, v6
	v_fma_f32 v3, -v3, v8, v7
	v_div_fmas_f32 v3, v3, v6, v8
	v_div_fixup_f32 v0, v3, v2, v51
	ds_write_b32 v27, v0 offset:11264
